# side-task entry and attention block seams wait only for the older LDS-DMA/q loads (counted vmcnt) instead of for the epilogue stores; plus lane-permuted P1 epilogue stores and row-contiguous side-task
# baseline (speedup 1.0000x reference)
; #define LAS __attribute__((address_space(3)))
; #define PG8_WAIT_V(n) asm volatile("s_waitcnt vmcnt(" #n ")" ::: "memory")
; #define PG8_BAR __builtin_amdgcn_s_barrier()
; template <class Epi, class Sched, int NSEG, bool ALIGN_EPI = true, bool AFTER_DRAIN = false>
; __device__ __forceinline__ void gemm_phase(LAS unsigned char* lds, const Gemm g, const Sched& S, const Epi& E) {
;     ...
;     PG8_WAIT_V(0);
;     if constexpr (!ALIGN_EPI) { if (wr == 0) PG8_BAR; }
;     PG8_BAR;
; __global__ void __launch_bounds__(NTHREADS, 2) fox_fwd(Args args) {
;     ...
;         for (int srep = 0; srep < SIDE_REPS; ++srep) for (int c = bx; c < 256; c += G) p1_side_task(c, (LAS unsigned char*)lds, XN, WIN, b_f, LF, Kb, Vb, P1b);
.LBB0_412:
	s_waitcnt vmcnt(8)
	s_barrier
	s_cmpk_gt_i32 s97, 0xff
	s_cbranch_scc1 .LBB0_432

; #define LAS __attribute__((address_space(3)))
; __device__ __forceinline__ unsigned cvt_pk_bf16(float lo, float hi) { unsigned r; asm volatile("v_cvt_pk_bf16_f32 %0, %1, %2" : "=v"(r) : "v"(lo), "v"(hi)); return r; }
; __device__ __forceinline__ float bf_lo(unsigned w) { return __uint_as_float(w << 16); }
; __device__ __forceinline__ float bf_hi(unsigned w) { return __uint_as_float(w & 0xffff0000u); }
; __device__ __forceinline__ int crow(int r, int hi) { return (r & 3) + 8 * (r >> 2) + 4 * hi; }
; __device__ __forceinline__ void fox_block(const BlockRef& cur, const BlockRef& nxt, char* lds, Seam& S, const int tid) {
;     ...
;     if (hi == 0) li_l[r32] = l_reg; asm volatile("s_waitcnt lgkmcnt(0)" ::: "memory");
;     float rli[16];
; #pragma unroll
;     for (int r = 0; r < 16; ++r) rli[r] = __builtin_amdgcn_rcpf(li_l[crow(r, hi)]);
;     typedef __attribute__((address_space(1))) bf16_t gbf16; typedef __attribute__((address_space(1))) u32x4 gu32x4;
;     LAS float* stg = (LAS float*)(lds3 + SLOT + wid * 4096);
;     const int er = lane >> 2, eq = lane & 3;
;     gbf16* obase = (gbf16*)(cur.O + (size_t)(wid * QBLK + er) * LD + 8 * eq); const gbf16* zbase = (const gbf16*)(cur.Z + (size_t)(wid * QBLK + er) * LD + 8 * eq);
; #pragma unroll
;     for (int d0 = 0; d0 < 4; ++d0) {
; #pragma unroll
;         for (int r = 0; r < 16; ++r) stg[crow(r, hi) * 32 + r32] = o[d0][r] * rli[r];
;         asm volatile("s_waitcnt lgkmcnt(0)" ::: "memory");
;         gbf16* op = obase; const gbf16* zp = zbase;
; #pragma unroll
;         for (int i = 0; i < 2; ++i) {
;             asm volatile("" : "+v"(op), "+v"(zp));
;             const f32x4 v0 = *(const LAS f32x4*)(stg + (er + 16 * i) * 32 + 8 * eq), v1 = *(const LAS f32x4*)(stg + (er + 16 * i) * 32 + 8 * eq + 4);
;             const u32x4 z = __builtin_nontemporal_load((const gu32x4*)(zp + d0 * 32));
;             u32x4 w; w.x = cvt_pk_bf16(v0.x * bf_lo(z.x), v0.y * bf_hi(z.x)); w.y = cvt_pk_bf16(v0.z * bf_lo(z.y), v0.w * bf_hi(z.y));
;             w.z = cvt_pk_bf16(v1.x * bf_lo(z.z), v1.y * bf_hi(z.z)); w.w = cvt_pk_bf16(v1.z * bf_lo(z.w), v1.w * bf_hi(z.w));
.LBB0_485:
	s_or_b64 exec, exec, s[2:3]
	s_waitcnt lgkmcnt(0)
	ds_read_b128 v[64:67], v131
	ds_read_b128 v[68:71], v131 offset:32
	v_readlane_b32 s0, v248, 54
	s_add_u32 s0, s0, s68
	v_readlane_b32 s1, v248, 56
	s_waitcnt lgkmcnt(0)
	v_rcp_f32_e32 v72, v64
	v_rcp_f32_e32 v73, v65
	v_rcp_f32_e32 v74, v66
	v_rcp_f32_e32 v75, v67
	v_rcp_f32_e32 v76, v68
	ds_read_b128 v[64:67], v131 offset:64
	v_rcp_f32_e32 v77, v69
	v_rcp_f32_e32 v78, v70
	v_rcp_f32_e32 v79, v71
	ds_read_b128 v[68:71], v131 offset:96
	s_addc_u32 s1, s1, s69
	v_readlane_b32 s2, v248, 42
	s_add_u32 s2, s2, s68
	v_readlane_b32 s3, v248, 43
	s_addc_u32 s3, s3, s69
	s_lshl_b32 s4, s70, 12
	s_add_i32 s4, s4, 0
	s_waitcnt lgkmcnt(0)
	v_rcp_f32_e32 v84, v68
	v_add3_u32 v68, s4, v133, v170
	v_rcp_f32_e32 v80, v64
	v_rcp_f32_e32 v81, v65
	v_mul_f32_e32 v48, v48, v72
	v_mul_f32_e32 v49, v49, v73
	v_add_u32_e32 v88, 0x4000, v68
	v_rcp_f32_e32 v82, v66
	v_rcp_f32_e32 v83, v67
	ds_write2_b32 v88, v48, v49 offset1:32
	v_mul_f32_e32 v48, v50, v74
	v_mul_f32_e32 v49, v51, v75
	v_rcp_f32_e32 v85, v69
	ds_write2_b32 v88, v48, v49 offset0:64 offset1:96
	v_mul_f32_e32 v48, v52, v76
	v_mul_f32_e32 v49, v53, v77
	v_add_u32_e32 v89, 0x4400, v68
	v_rcp_f32_e32 v86, v70
	v_rcp_f32_e32 v87, v71
	v_or_b32_e32 v64, s71, v191
	ds_write2_b32 v89, v48, v49 offset1:32
	v_mul_f32_e32 v48, v54, v78
	v_mul_f32_e32 v49, v55, v79
	v_ashrrev_i32_e32 v65, 31, v64
	ds_write2_b32 v89, v48, v49 offset0:64 offset1:96
	v_mul_f32_e32 v48, v56, v80
	v_mul_f32_e32 v49, v57, v81
	v_add_u32_e32 v90, 0x4800, v68
	v_lshlrev_b64 v[66:67], 12, v[64:65]
	ds_write2_b32 v90, v48, v49 offset1:32
	v_mul_f32_e32 v48, v58, v82
	v_mul_f32_e32 v49, v59, v83
	v_lshl_add_u64 v[64:65], s[0:1], 0, v[66:67]
	v_lshlrev_b32_e32 v128, 1, v132
	v_lshl_add_u64 v[66:67], s[2:3], 0, v[66:67]
	ds_write2_b32 v90, v48, v49 offset0:64 offset1:96
	v_mul_f32_e32 v48, v60, v84
	v_mul_f32_e32 v49, v61, v85
	v_add_u32_e32 v91, 0x4c00, v68
	v_lshl_add_u64 v[64:65], v[64:65], 0, v[128:129]
	v_lshl_add_u64 v[66:67], v[66:67], 0, v[128:129]
	ds_write2_b32 v91, v48, v49 offset1:32
	v_mul_f32_e32 v48, v62, v86
	v_mul_f32_e32 v49, v63, v87
	ds_write2_b32 v91, v48, v49 offset0:64 offset1:96
	v_mov_b64_e32 v[62:63], v[64:65]
	v_mov_b64_e32 v[68:69], v[66:67]
	s_waitcnt lgkmcnt(0)
	global_load_dwordx4 v[50:53], v[68:69], off nt
	v_add_co_u32_e32 v250, vcc, 0x10000, v68
	s_nop 1
	v_addc_co_u32_e32 v251, vcc, 0, v69, vcc
	global_load_dwordx4 v[222:225], v[250:251], off nt
	global_load_dwordx4 v[226:229], v[68:69], off offset:64 nt
	global_load_dwordx4 v[230:233], v[250:251], off offset:64 nt
	global_load_dwordx4 v[234:237], v[68:69], off offset:128 nt
	global_load_dwordx4 v[238:241], v[250:251], off offset:128 nt
	global_load_dwordx4 v[242:245], v[68:69], off offset:192 nt
	v_lshlrev_b32_e32 v48, 2, v132
	v_add3_u32 v48, s4, v48, v145
	ds_read_b128 v[54:57], v48 offset:16384
	ds_read_b128 v[58:61], v48 offset:16400
	s_mov_b64 s[0:1], 0x10000
	v_lshl_add_u64 v[70:71], v[62:63], 0, s[0:1]
	v_lshl_add_u64 v[68:69], v[68:69], 0, s[0:1]
	v_mul_f32_e32 v40, v40, v80
	v_mul_f32_e32 v41, v41, v81
	v_mul_f32_e32 v42, v42, v82
	v_mul_f32_e32 v43, v43, v83
	v_mul_f32_e32 v44, v44, v84
	v_mul_f32_e32 v45, v45, v85
	v_mul_f32_e32 v46, v46, v86
	v_mul_f32_e32 v47, v47, v87
	v_mul_f32_e32 v24, v24, v80
	v_mul_f32_e32 v25, v25, v81
	v_mul_f32_e32 v26, v26, v82
	v_mul_f32_e32 v27, v27, v83
	v_mul_f32_e32 v28, v28, v84
	v_mul_f32_e32 v29, v29, v85
	v_mul_f32_e32 v30, v30, v86
	v_mul_f32_e32 v31, v31, v87
	v_mul_f32_e32 v8, v8, v80
	v_mul_f32_e32 v9, v9, v81
	v_mul_f32_e32 v10, v10, v82
	v_mul_f32_e32 v11, v11, v83
	v_mul_f32_e32 v12, v12, v84
	v_mul_f32_e32 v13, v13, v85
	v_mul_f32_e32 v14, v14, v86
	v_mul_f32_e32 v15, v15, v87
	v_readlane_b32 s60, v247, 11
	s_add_i32 s60, s60, s96
	v_readlane_b32 s66, v247, 4
	v_readlane_b32 s68, v247, 6
	s_movk_i32 s6, 0x1010
	v_readlane_b32 s67, v247, 5
	v_readlane_b32 s69, v247, 7
	s_waitcnt vmcnt(6)
	v_lshlrev_b32_e32 v49, 16, v50
	v_and_b32_e32 v50, 0xffff0000, v50
	v_lshlrev_b32_e32 v92, 16, v51
	v_and_b32_e32 v51, 0xffff0000, v51
	v_lshlrev_b32_e32 v93, 16, v52
	v_and_b32_e32 v52, 0xffff0000, v52
	v_lshlrev_b32_e32 v94, 16, v53
	v_and_b32_e32 v53, 0xffff0000, v53
	s_waitcnt lgkmcnt(1)
	v_mul_f32_e32 v50, v55, v50
	v_mul_f32_e32 v51, v57, v51
	s_waitcnt lgkmcnt(0)
	v_mul_f32_e32 v52, v59, v52
	v_mul_f32_e32 v53, v61, v53
	v_mul_f32_e32 v49, v54, v49
	v_mul_f32_e32 v54, v56, v92
	v_mul_f32_e32 v55, v58, v93
	v_mul_f32_e32 v56, v60, v94
	v_cvt_pk_bf16_f32 v50, v49, v50
	v_cvt_pk_bf16_f32 v51, v54, v51
	v_cvt_pk_bf16_f32 v52, v55, v52
	v_cvt_pk_bf16_f32 v53, v56, v53
	global_store_dwordx4 v[62:63], v[50:53], off
	v_mul_f32_e32 v49, v32, v72
	v_mul_f32_e32 v58, v33, v73
	v_mul_f32_e32 v59, v34, v74
	v_mul_f32_e32 v60, v35, v75
	v_mul_f32_e32 v61, v36, v76
	v_mul_f32_e32 v62, v37, v77
	v_mul_f32_e32 v63, v38, v78
	v_mul_f32_e32 v68, v39, v79
	ds_read_b128 v[32:35], v48 offset:18432
	ds_read_b128 v[36:39], v48 offset:18448
	v_mov_b64_e32 v[54:55], v[64:65]
	v_mov_b64_e32 v[56:57], v[66:67]
	s_waitcnt vmcnt(6)
	v_mov_b32_e32 v50, v222
	v_mov_b32_e32 v51, v223
	v_mov_b32_e32 v52, v224
	v_mov_b32_e32 v53, v225
	global_load_dwordx4 v[222:225], v[250:251], off offset:192 nt
	v_lshlrev_b32_e32 v69, 16, v50
	v_and_b32_e32 v50, 0xffff0000, v50
	v_lshlrev_b32_e32 v92, 16, v51
	v_and_b32_e32 v51, 0xffff0000, v51
	v_lshlrev_b32_e32 v93, 16, v52
	v_and_b32_e32 v52, 0xffff0000, v52
	v_lshlrev_b32_e32 v94, 16, v53
	v_and_b32_e32 v53, 0xffff0000, v53
	s_waitcnt lgkmcnt(1)
	v_mul_f32_e32 v32, v32, v69
	v_mul_f32_e32 v33, v33, v50
	v_mul_f32_e32 v34, v34, v92
	v_mul_f32_e32 v35, v35, v51
	s_waitcnt lgkmcnt(0)
; #define LAS __attribute__((address_space(3)))
; __device__ __forceinline__ unsigned cvt_pk_bf16(float lo, float hi) { unsigned r; asm volatile("v_cvt_pk_bf16_f32 %0, %1, %2" : "=v"(r) : "v"(lo), "v"(hi)); return r; }
; __device__ __forceinline__ float bf_lo(unsigned w) { return __uint_as_float(w << 16); }
; __device__ __forceinline__ float bf_hi(unsigned w) { return __uint_as_float(w & 0xffff0000u); }
; __device__ __forceinline__ int crow(int r, int hi) { return (r & 3) + 8 * (r >> 2) + 4 * hi; }
; __device__ __forceinline__ void fox_block(const BlockRef& cur, const BlockRef& nxt, char* lds, Seam& S, const int tid) {
;     ...
;     for (int d0 = 0; d0 < 4; ++d0) {
; #pragma unroll
;         for (int r = 0; r < 16; ++r) stg[crow(r, hi) * 32 + r32] = o[d0][r] * rli[r];
;         asm volatile("s_waitcnt lgkmcnt(0)" ::: "memory");
;         gbf16* op = obase; const gbf16* zp = zbase;
; #pragma unroll
;         for (int i = 0; i < 2; ++i) {
;             asm volatile("" : "+v"(op), "+v"(zp));
;             const f32x4 v0 = *(const LAS f32x4*)(stg + (er + 16 * i) * 32 + 8 * eq), v1 = *(const LAS f32x4*)(stg + (er + 16 * i) * 32 + 8 * eq + 4);
;             const u32x4 z = __builtin_nontemporal_load((const gu32x4*)(zp + d0 * 32));
;             u32x4 w; w.x = cvt_pk_bf16(v0.x * bf_lo(z.x), v0.y * bf_hi(z.x)); w.y = cvt_pk_bf16(v0.z * bf_lo(z.y), v0.w * bf_hi(z.y));
;             w.z = cvt_pk_bf16(v1.x * bf_lo(z.z), v1.y * bf_hi(z.z)); w.w = cvt_pk_bf16(v1.z * bf_lo(z.w), v1.w * bf_hi(z.w));
;             *(gu32x4*)(op + d0 * 32) = w;
;             op += 16 * LD; zp += 16 * LD; }
;         asm volatile("s_waitcnt lgkmcnt(0)" ::: "memory"); }
	v_mul_f32_e32 v36, v36, v93
	v_mul_f32_e32 v37, v37, v52
	v_mul_f32_e32 v38, v38, v94
	v_mul_f32_e32 v39, v39, v53
	v_cvt_pk_bf16_f32 v32, v32, v33
	v_cvt_pk_bf16_f32 v33, v34, v35
	v_cvt_pk_bf16_f32 v34, v36, v37
	v_cvt_pk_bf16_f32 v35, v38, v39
	global_store_dwordx4 v[70:71], v[32:35], off
	s_waitcnt lgkmcnt(0)
	ds_write2_b32 v88, v49, v58 offset1:32
	ds_write2_b32 v88, v59, v60 offset0:64 offset1:96
	ds_write2_b32 v89, v61, v62 offset1:32
	ds_write2_b32 v89, v63, v68 offset0:64 offset1:96
	ds_write2_b32 v90, v40, v41 offset1:32
	ds_write2_b32 v90, v42, v43 offset0:64 offset1:96
	ds_write2_b32 v91, v44, v45 offset1:32
	ds_write2_b32 v91, v46, v47 offset0:64 offset1:96
	s_waitcnt lgkmcnt(0)
	ds_read_b128 v[36:39], v48 offset:16384
	ds_read_b128 v[40:43], v48 offset:16400
	v_lshl_add_u64 v[44:45], v[54:55], 0, s[0:1]
	v_lshl_add_u64 v[46:47], v[56:57], 0, s[0:1]
	s_waitcnt vmcnt(7)
	v_mov_b32_e32 v32, v226
	v_mov_b32_e32 v33, v227
	v_mov_b32_e32 v34, v228
	v_mov_b32_e32 v35, v229
	v_lshlrev_b32_e32 v49, 16, v32
	v_and_b32_e32 v32, 0xffff0000, v32
	v_lshlrev_b32_e32 v50, 16, v33
	v_and_b32_e32 v33, 0xffff0000, v33
	v_lshlrev_b32_e32 v51, 16, v34
	v_and_b32_e32 v34, 0xffff0000, v34
	v_lshlrev_b32_e32 v52, 16, v35
	v_and_b32_e32 v35, 0xffff0000, v35
	s_waitcnt lgkmcnt(1)
	v_mul_f32_e32 v32, v37, v32
	v_mul_f32_e32 v33, v39, v33
	s_waitcnt lgkmcnt(0)
	v_mul_f32_e32 v34, v41, v34
	v_mul_f32_e32 v35, v43, v35
	v_mul_f32_e32 v36, v36, v49
	v_mul_f32_e32 v37, v38, v50
	v_mul_f32_e32 v38, v40, v51
	v_mul_f32_e32 v39, v42, v52
	v_cvt_pk_bf16_f32 v32, v36, v32
	v_cvt_pk_bf16_f32 v33, v37, v33
	v_cvt_pk_bf16_f32 v34, v38, v34
	v_cvt_pk_bf16_f32 v35, v39, v35
	global_store_dwordx4 v[54:55], v[32:35], off offset:64
	v_mul_f32_e32 v40, v16, v72
	v_mul_f32_e32 v41, v17, v73
	v_mul_f32_e32 v42, v18, v74
	v_mul_f32_e32 v43, v19, v75
	v_mul_f32_e32 v46, v20, v76
	v_mul_f32_e32 v47, v21, v77
	v_mul_f32_e32 v49, v22, v78
	v_mul_f32_e32 v50, v23, v79
	ds_read_b128 v[16:19], v48 offset:18432
	ds_read_b128 v[20:23], v48 offset:18448
	v_mov_b64_e32 v[36:37], v[64:65]
	v_mov_b64_e32 v[38:39], v[66:67]
	s_waitcnt vmcnt(7)
	v_mov_b32_e32 v32, v230
	v_mov_b32_e32 v33, v231
	v_mov_b32_e32 v34, v232
	v_mov_b32_e32 v35, v233
	v_lshlrev_b32_e32 v51, 16, v32
	v_and_b32_e32 v32, 0xffff0000, v32
	v_lshlrev_b32_e32 v52, 16, v33
	v_and_b32_e32 v33, 0xffff0000, v33
	v_lshlrev_b32_e32 v53, 16, v34
	v_and_b32_e32 v34, 0xffff0000, v34
	v_lshlrev_b32_e32 v54, 16, v35
	v_and_b32_e32 v35, 0xffff0000, v35
	s_waitcnt lgkmcnt(1)
	v_mul_f32_e32 v16, v16, v51
	v_mul_f32_e32 v17, v17, v32
	v_mul_f32_e32 v18, v18, v52
	v_mul_f32_e32 v19, v19, v33
	s_waitcnt lgkmcnt(0)
	v_mul_f32_e32 v20, v20, v53
	v_mul_f32_e32 v21, v21, v34
	v_mul_f32_e32 v22, v22, v54
	v_mul_f32_e32 v23, v23, v35
	v_cvt_pk_bf16_f32 v16, v16, v17
	v_cvt_pk_bf16_f32 v17, v18, v19
	v_cvt_pk_bf16_f32 v18, v20, v21
	v_cvt_pk_bf16_f32 v19, v22, v23
	global_store_dwordx4 v[44:45], v[16:19], off offset:64
	s_waitcnt lgkmcnt(0)
	ds_write2_b32 v88, v40, v41 offset1:32
	ds_write2_b32 v88, v42, v43 offset0:64 offset1:96
	ds_write2_b32 v89, v46, v47 offset1:32
	ds_write2_b32 v89, v49, v50 offset0:64 offset1:96
	ds_write2_b32 v90, v24, v25 offset1:32
	ds_write2_b32 v90, v26, v27 offset0:64 offset1:96
	ds_write2_b32 v91, v28, v29 offset1:32
	ds_write2_b32 v91, v30, v31 offset0:64 offset1:96
	s_waitcnt lgkmcnt(0)
	ds_read_b128 v[20:23], v48 offset:16384
	ds_read_b128 v[24:27], v48 offset:16400
	v_lshl_add_u64 v[28:29], v[36:37], 0, s[0:1]
	v_lshl_add_u64 v[30:31], v[38:39], 0, s[0:1]
	s_waitcnt vmcnt(7)
	v_mov_b32_e32 v16, v234
	v_mov_b32_e32 v17, v235
	v_mov_b32_e32 v18, v236
	v_mov_b32_e32 v19, v237
	v_lshlrev_b32_e32 v32, 16, v16
	v_and_b32_e32 v16, 0xffff0000, v16
	v_lshlrev_b32_e32 v33, 16, v17
	v_and_b32_e32 v17, 0xffff0000, v17
	v_lshlrev_b32_e32 v34, 16, v18
	v_and_b32_e32 v18, 0xffff0000, v18
	v_lshlrev_b32_e32 v35, 16, v19
	v_and_b32_e32 v19, 0xffff0000, v19
	s_waitcnt lgkmcnt(1)
	v_mul_f32_e32 v16, v21, v16
	v_mul_f32_e32 v17, v23, v17
	s_waitcnt lgkmcnt(0)
; #define LAS __attribute__((address_space(3)))
; __device__ __forceinline__ unsigned cvt_pk_bf16(float lo, float hi) { unsigned r; asm volatile("v_cvt_pk_bf16_f32 %0, %1, %2" : "=v"(r) : "v"(lo), "v"(hi)); return r; }
; __device__ __forceinline__ float bf_lo(unsigned w) { return __uint_as_float(w << 16); }
; __device__ __forceinline__ float bf_hi(unsigned w) { return __uint_as_float(w & 0xffff0000u); }
; __device__ __forceinline__ int crow(int r, int hi) { return (r & 3) + 8 * (r >> 2) + 4 * hi; }
; #define WAITV_BAR(N) asm volatile("s_waitcnt vmcnt(" #N ") lgkmcnt(0)\n\ts_barrier" ::: "memory")
; __device__ __forceinline__ void fox_block(const BlockRef& cur, const BlockRef& nxt, char* lds, Seam& S, const int tid) {
;     ...
;     for (int d0 = 0; d0 < 4; ++d0) {
; #pragma unroll
;         for (int r = 0; r < 16; ++r) stg[crow(r, hi) * 32 + r32] = o[d0][r] * rli[r];
;         asm volatile("s_waitcnt lgkmcnt(0)" ::: "memory");
;         gbf16* op = obase; const gbf16* zp = zbase;
; #pragma unroll
;         for (int i = 0; i < 2; ++i) {
;             asm volatile("" : "+v"(op), "+v"(zp));
;             const f32x4 v0 = *(const LAS f32x4*)(stg + (er + 16 * i) * 32 + 8 * eq), v1 = *(const LAS f32x4*)(stg + (er + 16 * i) * 32 + 8 * eq + 4);
;             const u32x4 z = __builtin_nontemporal_load((const gu32x4*)(zp + d0 * 32));
;             u32x4 w; w.x = cvt_pk_bf16(v0.x * bf_lo(z.x), v0.y * bf_hi(z.x)); w.y = cvt_pk_bf16(v0.z * bf_lo(z.y), v0.w * bf_hi(z.y));
;             w.z = cvt_pk_bf16(v1.x * bf_lo(z.z), v1.y * bf_hi(z.z)); w.w = cvt_pk_bf16(v1.z * bf_lo(z.w), v1.w * bf_hi(z.w));
;             *(gu32x4*)(op + d0 * 32) = w;
;             op += 16 * LD; zp += 16 * LD; }
;         asm volatile("s_waitcnt lgkmcnt(0)" ::: "memory"); }
;     WAITV_BAR(0);
	v_mul_f32_e32 v18, v25, v18
	v_mul_f32_e32 v19, v27, v19
	v_mul_f32_e32 v20, v20, v32
	v_mul_f32_e32 v21, v22, v33
	v_mul_f32_e32 v22, v24, v34
	v_mul_f32_e32 v23, v26, v35
	v_cvt_pk_bf16_f32 v16, v20, v16
	v_cvt_pk_bf16_f32 v17, v21, v17
	v_cvt_pk_bf16_f32 v18, v22, v18
	v_cvt_pk_bf16_f32 v19, v23, v19
	global_store_dwordx4 v[36:37], v[16:19], off offset:128
	v_mul_f32_e32 v20, v0, v72
	v_mul_f32_e32 v21, v1, v73
	v_mul_f32_e32 v22, v2, v74
	v_mul_f32_e32 v23, v3, v75
	v_mul_f32_e32 v24, v4, v76
	v_mul_f32_e32 v25, v5, v77
	v_mul_f32_e32 v26, v6, v78
	v_mul_f32_e32 v27, v7, v79
	ds_read_b128 v[0:3], v48 offset:18432
	ds_read_b128 v[4:7], v48 offset:18448
	s_waitcnt vmcnt(7)
	v_mov_b32_e32 v16, v238
	v_mov_b32_e32 v17, v239
	v_mov_b32_e32 v18, v240
	v_mov_b32_e32 v19, v241
	v_lshlrev_b32_e32 v30, 16, v16
	v_and_b32_e32 v16, 0xffff0000, v16
	v_lshlrev_b32_e32 v31, 16, v17
	v_and_b32_e32 v17, 0xffff0000, v17
	v_lshlrev_b32_e32 v32, 16, v18
	v_and_b32_e32 v18, 0xffff0000, v18
	v_lshlrev_b32_e32 v33, 16, v19
	v_and_b32_e32 v19, 0xffff0000, v19
	s_waitcnt lgkmcnt(1)
	v_mul_f32_e32 v0, v0, v30
	v_mul_f32_e32 v1, v1, v16
	v_mul_f32_e32 v2, v2, v31
	v_mul_f32_e32 v3, v3, v17
	s_waitcnt lgkmcnt(0)
	v_mul_f32_e32 v4, v4, v32
	v_mul_f32_e32 v5, v5, v18
	v_mul_f32_e32 v6, v6, v33
	v_mul_f32_e32 v7, v7, v19
	v_cvt_pk_bf16_f32 v0, v0, v1
	v_cvt_pk_bf16_f32 v1, v2, v3
	v_cvt_pk_bf16_f32 v2, v4, v5
	v_cvt_pk_bf16_f32 v3, v6, v7
	global_store_dwordx4 v[28:29], v[0:3], off offset:128
	s_waitcnt lgkmcnt(0)
	ds_write2_b32 v88, v20, v21 offset1:32
	ds_write2_b32 v88, v22, v23 offset0:64 offset1:96
	ds_write2_b32 v89, v24, v25 offset1:32
	ds_write2_b32 v89, v26, v27 offset0:64 offset1:96
	ds_write2_b32 v90, v8, v9 offset1:32
	ds_write2_b32 v90, v10, v11 offset0:64 offset1:96
	ds_write2_b32 v91, v12, v13 offset1:32
	ds_write2_b32 v91, v14, v15 offset0:64 offset1:96
	s_waitcnt lgkmcnt(0)
	ds_read_b128 v[4:7], v48 offset:16384
	ds_read_b128 v[8:11], v48 offset:16400
	v_lshl_add_u64 v[12:13], v[64:65], 0, s[0:1]
	v_lshl_add_u64 v[14:15], v[66:67], 0, s[0:1]
	v_readlane_b32 s0, v248, 61
	v_readlane_b32 s1, v248, 62
	s_add_i32 s0, s0, s1
	s_cmpk_lt_i32 s60, 0x100
	v_writelane_b32 v248, s0, 61
	s_waitcnt vmcnt(7)
	v_mov_b32_e32 v0, v242
	v_mov_b32_e32 v1, v243
	v_mov_b32_e32 v2, v244
	v_mov_b32_e32 v3, v245
	v_lshlrev_b32_e32 v16, 16, v0
	v_and_b32_e32 v0, 0xffff0000, v0
	v_lshlrev_b32_e32 v17, 16, v1
	v_and_b32_e32 v1, 0xffff0000, v1
	v_lshlrev_b32_e32 v18, 16, v2
	v_and_b32_e32 v2, 0xffff0000, v2
	v_lshlrev_b32_e32 v19, 16, v3
	v_and_b32_e32 v3, 0xffff0000, v3
	s_waitcnt lgkmcnt(1)
	v_mul_f32_e32 v0, v5, v0
	v_mul_f32_e32 v1, v7, v1
	s_waitcnt lgkmcnt(0)
	v_mul_f32_e32 v2, v9, v2
	v_mul_f32_e32 v3, v11, v3
	v_mul_f32_e32 v4, v4, v16
	v_mul_f32_e32 v5, v6, v17
	v_mul_f32_e32 v6, v8, v18
	v_mul_f32_e32 v7, v10, v19
	v_cvt_pk_bf16_f32 v0, v4, v0
	v_cvt_pk_bf16_f32 v1, v5, v1
	v_cvt_pk_bf16_f32 v2, v6, v2
	v_cvt_pk_bf16_f32 v3, v7, v3
	global_store_dwordx4 v[64:65], v[0:3], off offset:192
	ds_read_b128 v[4:7], v48 offset:18432
	ds_read_b128 v[8:11], v48 offset:18448
	s_waitcnt vmcnt(6)
	v_mov_b32_e32 v0, v222
	v_mov_b32_e32 v1, v223
	v_mov_b32_e32 v2, v224
	v_mov_b32_e32 v3, v225
	v_lshlrev_b32_e32 v14, 16, v0
	v_and_b32_e32 v0, 0xffff0000, v0
	v_lshlrev_b32_e32 v15, 16, v1
	v_and_b32_e32 v1, 0xffff0000, v1
	v_lshlrev_b32_e32 v16, 16, v2
	v_and_b32_e32 v2, 0xffff0000, v2
	v_lshlrev_b32_e32 v17, 16, v3
	v_and_b32_e32 v3, 0xffff0000, v3
	s_waitcnt lgkmcnt(1)
	v_mul_f32_e32 v0, v5, v0
	v_mul_f32_e32 v1, v7, v1
	s_waitcnt lgkmcnt(0)
	v_mul_f32_e32 v2, v9, v2
	v_mul_f32_e32 v3, v11, v3
	v_mul_f32_e32 v4, v4, v14
	v_mul_f32_e32 v5, v6, v15
	v_mul_f32_e32 v6, v8, v16
	v_mul_f32_e32 v7, v10, v17
	v_cvt_pk_bf16_f32 v0, v4, v0
	v_cvt_pk_bf16_f32 v1, v5, v1
	v_cvt_pk_bf16_f32 v2, v6, v2
	v_cvt_pk_bf16_f32 v3, v7, v3
	global_store_dwordx4 v[12:13], v[0:3], off offset:192
	s_waitcnt lgkmcnt(0)
	s_waitcnt vmcnt(8) lgkmcnt(0)
	s_barrier
	s_cbranch_scc0 .LBB0_590

; #define SBAR() __builtin_amdgcn_sched_barrier(0)
; #define PV_RD(d0, kh, X) do { constexpr int b_ = v_rd_off(d0, 2 * (kh), 0); TRRD(X##l0, b_); TRRD(X##h0, b_ + 2048); TRRD(X##l1, b_ + 4096); TRRD(X##h1, b_ + 6144); } while (0)
; #define PV_MM(d0, X, PA, PB) do { \
;         o[d0] = __builtin_amdgcn_mfma_f32_32x32x16_bf16(PA, (bf16x8){X##l0[0], X##l0[1], X##l0[2], X##l0[3], X##h0[0], X##h0[1], X##h0[2], X##h0[3]}, o[d0], 0, 0, 0);   \
;         o[d0] = __builtin_amdgcn_mfma_f32_32x32x16_bf16(PB, (bf16x8){X##l1[0], X##l1[1], X##l1[2], X##l1[3], X##h1[0], X##h1[1], X##h1[2], X##h1[3]}, o[d0], 0, 0, 0); } while (0)
; #define PV_W4() do { asm volatile("s_waitcnt lgkmcnt(4)" ::: "memory"); SBAR(); } while (0)
; #define PV_W0() do { asm volatile("s_waitcnt lgkmcnt(0)" ::: "memory"); SBAR(); } while (0)
; __device__ __forceinline__ void finishSM(f32x16& p0, f32x16& p1, float alpha, float& l_reg, bf16x8& pa0, bf16x8& pa1, bf16x8& pa2, bf16x8& pa3) {
; #pragma unroll
;     for (int r = 0; r < 16; ++r) p1[r] = __builtin_amdgcn_exp2f(p1[r]);
;     float ps = 0;
; #pragma unroll
;     for (int r = 0; r < 16; ++r) ps += p0[r];
; #pragma unroll
;     for (int r = 0; r < 16; ++r) ps += p1[r];
;     { auto rr = __builtin_amdgcn_permlane32_swap(__float_as_uint(ps), __float_as_uint(ps), false, false);
;       ps = __uint_as_float(rr[0]) + __uint_as_float(rr[1]); }
;     l_reg = l_reg * alpha + ps;
;     ...
;     PK4(p0, 0, pa0); PK4(p0, 8, pa1); PK4(p1, 0, pa2); PK4(p1, 8, pa3);
; __device__ __forceinline__ void pv_tile(f32x16* o, int vb0, bf16x8 pa0, bf16x8 pa1, bf16x8 pa2, bf16x8 pa3) {
;     ...
;     s16x4 al0, al1, ah0, ah1, bl0, bl1, bh0, bh1;
;     PV_RD(0, 0, a);
;     PV_RD(0, 1, b); PV_W4(); PV_MM(0, a, pa0, pa1); SBAR();
;     PV_RD(1, 0, a); PV_W4(); PV_MM(0, b, pa2, pa3); SBAR();
;     PV_RD(1, 1, b); PV_W4(); PV_MM(1, a, pa0, pa1); SBAR();
;     PV_RD(2, 0, a); PV_W4(); PV_MM(1, b, pa2, pa3); SBAR();
;     PV_RD(2, 1, b); PV_W4(); PV_MM(2, a, pa0, pa1); SBAR();
;     PV_RD(3, 0, a); PV_W4(); PV_MM(2, b, pa2, pa3); SBAR();
;     PV_RD(3, 1, b); PV_W4(); PV_MM(3, a, pa0, pa1); SBAR();
;     PV_W0(); PV_MM(3, b, pa2, pa3);
.LBB0_553:
	v_add_f32_e32 v64, 0, v221
	v_add_f32_e32 v64, v236, v64
	v_add_f32_e32 v64, v233, v64
	v_add_f32_e32 v64, v235, v64
	v_add_f32_e32 v64, v231, v64
	v_add_f32_e32 v64, v234, v64
	v_add_f32_e32 v64, v230, v64
	v_add_f32_e32 v64, v232, v64
	v_add_f32_e32 v64, v227, v64
	v_add_f32_e32 v64, v229, v64
	v_add_f32_e32 v64, v225, v64
	v_add_f32_e32 v64, v228, v64
	v_exp_f32_e32 v74, v168
	v_add_f32_e32 v64, v223, v64
	v_exp_f32_e32 v75, v169
	v_add_f32_e32 v64, v226, v64
	v_exp_f32_e32 v76, v172
	v_add_f32_e32 v64, v222, v64
	v_exp_f32_e32 v77, v173
	v_add_f32_e32 v64, v224, v64
	v_exp_f32_e32 v78, v176
	v_add_f32_e32 v64, v74, v64
	v_exp_f32_e32 v79, v177
	v_add_f32_e32 v64, v75, v64
	v_exp_f32_e32 v80, v166
	v_add_f32_e32 v64, v76, v64
	v_exp_f32_e32 v81, v167
	v_add_f32_e32 v64, v77, v64
	v_exp_f32_e32 v82, v170
	v_add_f32_e32 v64, v78, v64
	v_exp_f32_e32 v83, v171
	v_add_f32_e32 v64, v79, v64
	v_exp_f32_e32 v84, v174
	v_add_f32_e32 v64, v80, v64
	v_exp_f32_e32 v85, v175
	v_add_f32_e32 v64, v81, v64
	v_exp_f32_e32 v86, v178
	v_add_f32_e32 v64, v82, v64
	v_exp_f32_e32 v87, v179
	v_add_f32_e32 v64, v83, v64
	v_readlane_b32 s7, v247, 12
	v_readlane_b32 s2, v247, 13
	v_exp_f32_e32 v88, v164
	v_add_f32_e32 v64, v84, v64
	s_or_b32 s2, s7, s2
	v_exp_f32_e32 v89, v165
	v_add_f32_e32 v64, v85, v64
	s_ashr_i32 s3, s2, 31
	v_readlane_b32 s4, v248, 63
	v_add_f32_e32 v64, v86, v64
	s_lshl_b64 s[2:3], s[2:3], 11
	v_readlane_b32 s5, v247, 0
	v_add_f32_e32 v64, v87, v64
	s_or_b64 s[2:3], s[2:3], s[4:5]
	v_add_f32_e32 v64, v88, v64
	s_lshl_b64 s[68:69], s[2:3], 1
	v_readlane_b32 s93, v247, 10
	v_add_f32_e32 v64, v89, v64
	s_add_u32 s2, s93, s68
	v_readlane_b32 s3, v248, 37
	v_mov_b32_e32 v65, v64
	s_addc_u32 s3, s3, s69
	s_nop 0
	v_permlane32_swap_b32_e32 v64, v65
	v_cvt_pk_bf16_f32 v66, v221, v236
	v_cvt_pk_bf16_f32 v67, v233, v235
	v_cvt_pk_bf16_f32 v68, v231, v234
	v_cvt_pk_bf16_f32 v69, v230, v232
	v_cvt_pk_bf16_f32 v70, v227, v229
	v_cvt_pk_bf16_f32 v71, v225, v228
	v_cvt_pk_bf16_f32 v72, v223, v226
	v_cvt_pk_bf16_f32 v73, v222, v224
	v_cvt_pk_bf16_f32 v74, v74, v75
	v_cvt_pk_bf16_f32 v75, v76, v77
	v_cvt_pk_bf16_f32 v76, v78, v79
	v_cvt_pk_bf16_f32 v77, v80, v81
	v_cvt_pk_bf16_f32 v78, v82, v83
	v_cvt_pk_bf16_f32 v79, v84, v85
	v_cvt_pk_bf16_f32 v80, v86, v87
	v_cvt_pk_bf16_f32 v81, v88, v89
	s_nop 0
	v_permlane32_swap_b32_e32 v66, v68
	v_permlane32_swap_b32_e32 v67, v69
	v_permlane32_swap_b32_e32 v70, v72
	v_permlane32_swap_b32_e32 v71, v73
	v_permlane32_swap_b32_e32 v74, v76
	v_permlane32_swap_b32_e32 v75, v77
	v_permlane32_swap_b32_e32 v78, v80
	v_permlane32_swap_b32_e32 v79, v81
	v_add_u32_e32 v98, s76, v192
	ds_read_b64_tr_b16 v[82:83], v98 offset:0
	ds_read_b64_tr_b16 v[84:85], v98 offset:0x800
	ds_read_b64_tr_b16 v[86:87], v98 offset:0x1000
	ds_read_b64_tr_b16 v[88:89], v98 offset:0x1800
	ds_read_b64_tr_b16 v[90:91], v98 offset:0x2000
	ds_read_b64_tr_b16 v[92:93], v98 offset:0x2800
	ds_read_b64_tr_b16 v[94:95], v98 offset:0x3000
	ds_read_b64_tr_b16 v[96:97], v98 offset:0x3800
	s_waitcnt lgkmcnt(4)
	s_nop 0
	v_mfma_f32_32x32x16_bf16 v[48:63], v[66:69], v[82:85], v[48:63]
	v_mfma_f32_32x32x16_bf16 v[48:63], v[70:73], v[86:89], v[48:63]
	ds_read_b64_tr_b16 v[82:83], v98 offset:0x200
	ds_read_b64_tr_b16 v[84:85], v98 offset:0xa00
	ds_read_b64_tr_b16 v[86:87], v98 offset:0x1200
	ds_read_b64_tr_b16 v[88:89], v98 offset:0x1a00
	s_waitcnt lgkmcnt(4)
	v_mfma_f32_32x32x16_bf16 v[48:63], v[74:77], v[90:93], v[48:63]
	v_mfma_f32_32x32x16_bf16 v[48:63], v[78:81], v[94:97], v[48:63]
	ds_read_b64_tr_b16 v[90:91], v98 offset:0x2200
	ds_read_b64_tr_b16 v[92:93], v98 offset:0x2a00
	ds_read_b64_tr_b16 v[94:95], v98 offset:0x3200
	ds_read_b64_tr_b16 v[96:97], v98 offset:0x3a00
	s_waitcnt lgkmcnt(4)
	v_mfma_f32_32x32x16_bf16 v[32:47], v[66:69], v[82:85], v[32:47]
	v_mfma_f32_32x32x16_bf16 v[32:47], v[70:73], v[86:89], v[32:47]
	ds_read_b64_tr_b16 v[82:83], v98 offset:0x400
	ds_read_b64_tr_b16 v[84:85], v98 offset:0xc00
	ds_read_b64_tr_b16 v[86:87], v98 offset:0x1400
	ds_read_b64_tr_b16 v[88:89], v98 offset:0x1c00
	s_waitcnt lgkmcnt(4)
	v_mfma_f32_32x32x16_bf16 v[32:47], v[74:77], v[90:93], v[32:47]
	v_mfma_f32_32x32x16_bf16 v[32:47], v[78:81], v[94:97], v[32:47]
	ds_read_b64_tr_b16 v[90:91], v98 offset:0x2400
	ds_read_b64_tr_b16 v[92:93], v98 offset:0x2c00
	ds_read_b64_tr_b16 v[94:95], v98 offset:0x3400
	ds_read_b64_tr_b16 v[96:97], v98 offset:0x3c00
	s_waitcnt lgkmcnt(4)
	v_mfma_f32_32x32x16_bf16 v[16:31], v[66:69], v[82:85], v[16:31]
	v_mfma_f32_32x32x16_bf16 v[16:31], v[70:73], v[86:89], v[16:31]
	ds_read_b64_tr_b16 v[82:83], v98 offset:0x600
	ds_read_b64_tr_b16 v[84:85], v98 offset:0xe00
	ds_read_b64_tr_b16 v[86:87], v98 offset:0x1600
	ds_read_b64_tr_b16 v[88:89], v98 offset:0x1e00
	s_waitcnt lgkmcnt(4)
	v_mfma_f32_32x32x16_bf16 v[16:31], v[74:77], v[90:93], v[16:31]
	v_mfma_f32_32x32x16_bf16 v[16:31], v[78:81], v[94:97], v[16:31]
	ds_read_b64_tr_b16 v[90:91], v98 offset:0x2600
	ds_read_b64_tr_b16 v[92:93], v98 offset:0x2e00
	ds_read_b64_tr_b16 v[94:95], v98 offset:0x3600
	ds_read_b64_tr_b16 v[96:97], v98 offset:0x3e00
	s_waitcnt lgkmcnt(4)
	v_mfma_f32_32x32x16_bf16 v[0:15], v[66:69], v[82:85], v[0:15]
	v_mfma_f32_32x32x16_bf16 v[0:15], v[70:73], v[86:89], v[0:15]
	s_waitcnt lgkmcnt(0)
	v_mfma_f32_32x32x16_bf16 v[0:15], v[74:77], v[90:93], v[0:15]
	v_mfma_f32_32x32x16_bf16 v[0:15], v[78:81], v[94:97], v[0:15]
	v_lshl_add_u64 v[66:67], s[2:3], 0, v[132:133]
	v_mov_b32_e32 v147, v129
	s_waitcnt vmcnt(0) lgkmcnt(0)
	s_barrier
; #define LAS __attribute__((address_space(3)))
; __device__ __forceinline__ unsigned cvt_pk_bf16(float lo, float hi) { unsigned r; asm volatile("v_cvt_pk_bf16_f32 %0, %1, %2" : "=v"(r) : "v"(lo), "v"(hi)); return r; }
; __device__ __forceinline__ float bf_lo(unsigned w) { return __uint_as_float(w << 16); }
; __device__ __forceinline__ float bf_hi(unsigned w) { return __uint_as_float(w & 0xffff0000u); }
; #define SBAR() __builtin_amdgcn_sched_barrier(0)
; __device__ __forceinline__ void fox_block(const BlockRef& cur, const BlockRef& nxt, char* lds, Seam& S, const int tid) {
;     ...
;     { const bf16_t* Kh = nxt.K; const bf16_t* Vh = nxt.V;
; #pragma unroll
;       for (int d0 = 0; d0 < 8; ++d0) S.qr[d0] = load8(nxt.Q + (size_t)(wid * QBLK + r32) * LD + d0 * 16 + hi * 8);
;       SBAR(); DMA_K(0, 0); DMA_K(1, SLOT); DMA_V(0, 0); SBAR(); }
;     if (hi == 0) li_l[r32] = l_reg; asm volatile("s_waitcnt lgkmcnt(0)" ::: "memory");
;     float rli[16];
; #pragma unroll
;     for (int r = 0; r < 16; ++r) rli[r] = __builtin_amdgcn_rcpf(li_l[crow(r, hi)]);
;     typedef __attribute__((address_space(1))) bf16_t gbf16; typedef __attribute__((address_space(1))) u32x4 gu32x4;
;     LAS float* stg = (LAS float*)(lds3 + SLOT + wid * 4096);
;     const int er = lane >> 2, eq = lane & 3;
;     gbf16* obase = (gbf16*)(cur.O + (size_t)(wid * QBLK + er) * LD + 8 * eq); const gbf16* zbase = (const gbf16*)(cur.Z + (size_t)(wid * QBLK + er) * LD + 8 * eq);
; #pragma unroll
;     for (int d0 = 0; d0 < 4; ++d0) {
; #pragma unroll
;         for (int r = 0; r < 16; ++r) stg[crow(r, hi) * 32 + r32] = o[d0][r] * rli[r];
;         asm volatile("s_waitcnt lgkmcnt(0)" ::: "memory");
;         gbf16* op = obase; const gbf16* zp = zbase;
; #pragma unroll
;         for (int i = 0; i < 2; ++i) {
;             asm volatile("" : "+v"(op), "+v"(zp));
;             const f32x4 v0 = *(const LAS f32x4*)(stg + (er + 16 * i) * 32 + 8 * eq), v1 = *(const LAS f32x4*)(stg + (er + 16 * i) * 32 + 8 * eq + 4);
;             const u32x4 z = __builtin_nontemporal_load((const gu32x4*)(zp + d0 * 32));
;             u32x4 w; w.x = cvt_pk_bf16(v0.x * bf_lo(z.x), v0.y * bf_hi(z.x)); w.y = cvt_pk_bf16(v0.z * bf_lo(z.y), v0.w * bf_hi(z.y));
;             w.z = cvt_pk_bf16(v1.x * bf_lo(z.z), v1.y * bf_hi(z.z)); w.w = cvt_pk_bf16(v1.z * bf_lo(z.w), v1.w * bf_hi(z.w));
	v_lshl_add_u64 v[66:67], v[66:67], 0, v[146:147]
	global_load_dwordx4 v[96:99], v[66:67], off
	global_load_dwordx4 v[100:103], v[66:67], off offset:32
	global_load_dwordx4 v[104:107], v[66:67], off offset:64
	global_load_dwordx4 v[108:111], v[66:67], off offset:96
	global_load_dwordx4 v[112:115], v[66:67], off offset:128
	global_load_dwordx4 v[116:119], v[66:67], off offset:160
	global_load_dwordx4 v[120:123], v[66:67], off offset:192
	global_load_dwordx4 v[124:127], v[66:67], off offset:224
	v_readlane_b32 s2, v247, 15
	s_mov_b32 m0, s2
	v_readlane_b32 s2, v247, 16
	global_load_lds_dwordx4 v[144:145], off
	s_mov_b32 m0, s2
	v_readlane_b32 s2, v247, 17
	global_load_lds_dwordx4 v[142:143], off
	s_mov_b32 m0, s2
	v_readlane_b32 s2, v247, 18
	global_load_lds_dwordx4 v[136:137], off
	s_mov_b32 m0, s2
	v_readlane_b32 s2, v247, 19
	global_load_lds_dwordx4 v[138:139], off
	s_mov_b32 m0, s70
	s_nop 0
	global_load_lds_dwordx4 v[140:141], off
	s_mov_b32 m0, s2
	s_nop 0
	global_load_lds_dwordx4 v[134:135], off
	s_and_saveexec_b64 s[2:3], s[0:1]
	v_add_f32_e32 v64, v64, v65
	v_fmac_f32_e32 v64, v215, v158
	ds_write_b32 v214, v64
	s_or_b64 exec, exec, s[2:3]
	s_waitcnt lgkmcnt(0)
	ds_read_b128 v[64:67], v131
	ds_read_b128 v[68:71], v131 offset:32
	v_readlane_b32 s2, v248, 42
	s_add_u32 s2, s2, s78
	v_readlane_b32 s3, v248, 43
	s_waitcnt lgkmcnt(0)
	v_rcp_f32_e32 v72, v64
	v_rcp_f32_e32 v73, v65
	v_rcp_f32_e32 v74, v66
	v_rcp_f32_e32 v75, v67
	v_rcp_f32_e32 v76, v68
	ds_read_b128 v[64:67], v131 offset:64
	v_rcp_f32_e32 v77, v69
	v_rcp_f32_e32 v78, v70
	v_rcp_f32_e32 v79, v71
	ds_read_b128 v[68:71], v131 offset:96
	s_addc_u32 s3, s3, s79
	v_readlane_b32 s4, v248, 54
	s_add_u32 s4, s4, s78
	v_readlane_b32 s5, v248, 56
	v_readlane_b32 s6, v247, 14
	s_addc_u32 s5, s5, s79
	s_lshl_b32 s6, s6, 12
	s_waitcnt lgkmcnt(0)
	v_rcp_f32_e32 v84, v68
	s_add_i32 s6, s6, 0
	v_lshlrev_b32_e32 v68, 3, v155
	v_lshlrev_b32_e32 v133, 2, v199
	v_lshlrev_b32_e32 v170, 9, v213
	v_and_b32_e32 v132, 24, v68
	v_add3_u32 v68, s6, v133, v170
	v_rcp_f32_e32 v80, v64
	v_rcp_f32_e32 v81, v65
	v_mul_f32_e32 v48, v48, v72
	v_mul_f32_e32 v49, v49, v73
	v_add_u32_e32 v86, 0x4000, v68
	v_rcp_f32_e32 v82, v66
	v_rcp_f32_e32 v83, v67
	ds_write2_b32 v86, v48, v49 offset1:32
	v_mul_f32_e32 v48, v50, v74
	v_mul_f32_e32 v49, v51, v75
	v_rcp_f32_e32 v85, v69
	ds_write2_b32 v86, v48, v49 offset0:64 offset1:96
	v_mul_f32_e32 v48, v52, v76
	v_mul_f32_e32 v49, v53, v77
	v_add_u32_e32 v87, 0x4400, v68
	v_rcp_f32_e32 v70, v70
	v_rcp_f32_e32 v71, v71
	v_or_b32_e32 v64, s77, v191
	ds_write2_b32 v87, v48, v49 offset1:32
	v_mul_f32_e32 v48, v54, v78
	v_mul_f32_e32 v49, v55, v79
	v_ashrrev_i32_e32 v65, 31, v64
	ds_write2_b32 v87, v48, v49 offset0:64 offset1:96
	v_mul_f32_e32 v48, v56, v80
	v_mul_f32_e32 v49, v57, v81
	v_add_u32_e32 v88, 0x4800, v68
	v_lshlrev_b64 v[66:67], 12, v[64:65]
	ds_write2_b32 v88, v48, v49 offset1:32
	v_mul_f32_e32 v48, v58, v82
	v_mul_f32_e32 v49, v59, v83
	v_lshl_add_u64 v[64:65], s[4:5], 0, v[66:67]
	v_lshlrev_b32_e32 v128, 1, v132
	v_lshl_add_u64 v[66:67], s[2:3], 0, v[66:67]
	ds_write2_b32 v88, v48, v49 offset0:64 offset1:96
	v_mul_f32_e32 v48, v60, v84
	v_mul_f32_e32 v49, v61, v85
	v_add_u32_e32 v89, 0x4c00, v68
	v_lshl_add_u64 v[64:65], v[64:65], 0, v[128:129]
	v_lshl_add_u64 v[66:67], v[66:67], 0, v[128:129]
	ds_write2_b32 v89, v48, v49 offset1:32
	v_mul_f32_e32 v48, v62, v70
	v_mul_f32_e32 v49, v63, v71
	ds_write2_b32 v89, v48, v49 offset0:64 offset1:96
	v_mov_b64_e32 v[62:63], v[64:65]
	v_mov_b64_e32 v[68:69], v[66:67]
	s_waitcnt lgkmcnt(0)
	global_load_dwordx4 v[50:53], v[68:69], off nt
	v_add_co_u32_e32 v250, vcc, 0x10000, v68
	s_nop 1
	v_addc_co_u32_e32 v251, vcc, 0, v69, vcc
	global_load_dwordx4 v[222:225], v[250:251], off nt
	global_load_dwordx4 v[226:229], v[68:69], off offset:64 nt
	global_load_dwordx4 v[230:233], v[250:251], off offset:64 nt
	global_load_dwordx4 v[234:237], v[68:69], off offset:128 nt
	global_load_dwordx4 v[238:241], v[250:251], off offset:128 nt
	global_load_dwordx4 v[242:245], v[68:69], off offset:192 nt
	v_lshlrev_b32_e32 v145, 7, v191
	v_lshlrev_b32_e32 v48, 2, v132
	v_add3_u32 v48, s6, v48, v145
	ds_read_b128 v[54:57], v48 offset:16384
	ds_read_b128 v[58:61], v48 offset:16400
	s_mov_b64 s[2:3], 0x10000
	v_mul_f32_e32 v40, v40, v80
	v_mul_f32_e32 v41, v41, v81
	v_mul_f32_e32 v42, v42, v82
	v_mul_f32_e32 v43, v43, v83
	v_mul_f32_e32 v44, v44, v84
	v_mul_f32_e32 v45, v45, v85
	v_mul_f32_e32 v46, v46, v70
	v_mul_f32_e32 v47, v47, v71
	v_mul_f32_e32 v24, v24, v80
	v_mul_f32_e32 v25, v25, v81
	v_mul_f32_e32 v26, v26, v82
	v_mul_f32_e32 v27, v27, v83
	v_mul_f32_e32 v28, v28, v84
	v_mul_f32_e32 v29, v29, v85
	v_mul_f32_e32 v30, v30, v70
	v_mul_f32_e32 v31, v31, v71
	v_mul_f32_e32 v8, v8, v80
	v_mul_f32_e32 v9, v9, v81
	v_mul_f32_e32 v10, v10, v82
	v_mul_f32_e32 v11, v11, v83
	v_mul_f32_e32 v12, v12, v84
	v_mul_f32_e32 v13, v13, v85
	v_mul_f32_e32 v14, v14, v70
	v_mul_f32_e32 v15, v15, v71
	s_movk_i32 s6, 0x60
	s_or_b32 s4, s7, 64
	s_mov_b32 s87, 4
	s_lshr_b32 s89, s4, 6
	s_waitcnt vmcnt(6)
	v_lshlrev_b32_e32 v49, 16, v50
	v_and_b32_e32 v50, 0xffff0000, v50
	v_lshlrev_b32_e32 v90, 16, v51
	v_and_b32_e32 v51, 0xffff0000, v51
	v_lshlrev_b32_e32 v91, 16, v52
	v_and_b32_e32 v52, 0xffff0000, v52
	s_waitcnt lgkmcnt(1)
	v_mul_f32_e32 v50, v55, v50
	v_mul_f32_e32 v51, v57, v51
	v_lshlrev_b32_e32 v92, 16, v53
	v_and_b32_e32 v53, 0xffff0000, v53
	v_mul_f32_e32 v49, v54, v49
	v_mul_f32_e32 v54, v56, v90
	s_waitcnt lgkmcnt(0)
; #define LAS __attribute__((address_space(3)))
; __device__ __forceinline__ unsigned cvt_pk_bf16(float lo, float hi) { unsigned r; asm volatile("v_cvt_pk_bf16_f32 %0, %1, %2" : "=v"(r) : "v"(lo), "v"(hi)); return r; }
; __device__ __forceinline__ float bf_lo(unsigned w) { return __uint_as_float(w << 16); }
; __device__ __forceinline__ float bf_hi(unsigned w) { return __uint_as_float(w & 0xffff0000u); }
; __device__ __forceinline__ int crow(int r, int hi) { return (r & 3) + 8 * (r >> 2) + 4 * hi; }
; __device__ __forceinline__ void fox_block(const BlockRef& cur, const BlockRef& nxt, char* lds, Seam& S, const int tid) {
;     ...
;     for (int d0 = 0; d0 < 4; ++d0) {
; #pragma unroll
;         for (int r = 0; r < 16; ++r) stg[crow(r, hi) * 32 + r32] = o[d0][r] * rli[r];
;         asm volatile("s_waitcnt lgkmcnt(0)" ::: "memory");
;         gbf16* op = obase; const gbf16* zp = zbase;
; #pragma unroll
;         for (int i = 0; i < 2; ++i) {
;             asm volatile("" : "+v"(op), "+v"(zp));
;             const f32x4 v0 = *(const LAS f32x4*)(stg + (er + 16 * i) * 32 + 8 * eq), v1 = *(const LAS f32x4*)(stg + (er + 16 * i) * 32 + 8 * eq + 4);
;             const u32x4 z = __builtin_nontemporal_load((const gu32x4*)(zp + d0 * 32));
;             u32x4 w; w.x = cvt_pk_bf16(v0.x * bf_lo(z.x), v0.y * bf_hi(z.x)); w.y = cvt_pk_bf16(v0.z * bf_lo(z.y), v0.w * bf_hi(z.y));
;             w.z = cvt_pk_bf16(v1.x * bf_lo(z.z), v1.y * bf_hi(z.z)); w.w = cvt_pk_bf16(v1.z * bf_lo(z.w), v1.w * bf_hi(z.w));
;             *(gu32x4*)(op + d0 * 32) = w;
;             op += 16 * LD; zp += 16 * LD; }
;         asm volatile("s_waitcnt lgkmcnt(0)" ::: "memory"); }
	v_mul_f32_e32 v55, v58, v91
	v_mul_f32_e32 v52, v59, v52
	v_cvt_pk_bf16_f32 v50, v49, v50
	v_cvt_pk_bf16_f32 v51, v54, v51
	v_mul_f32_e32 v56, v60, v92
	v_cvt_pk_bf16_f32 v52, v55, v52
	v_mul_f32_e32 v49, v61, v53
	v_cvt_pk_bf16_f32 v53, v56, v49
	global_store_dwordx4 v[62:63], v[50:53], off
	v_lshl_add_u64 v[54:55], v[62:63], 0, s[2:3]
	v_mul_f32_e32 v49, v32, v72
	v_lshl_add_u64 v[50:51], v[68:69], 0, s[2:3]
	v_mul_f32_e32 v60, v33, v73
	v_mul_f32_e32 v61, v34, v74
	v_mul_f32_e32 v62, v35, v75
	v_mul_f32_e32 v63, v36, v76
	v_mul_f32_e32 v68, v37, v77
	v_mul_f32_e32 v69, v38, v78
	v_mul_f32_e32 v90, v39, v79
	ds_read_b128 v[32:35], v48 offset:18432
	ds_read_b128 v[36:39], v48 offset:18448
	v_mov_b64_e32 v[56:57], v[66:67]
	v_mov_b64_e32 v[58:59], v[64:65]
	s_waitcnt vmcnt(6)
	v_mov_b32_e32 v50, v222
	v_mov_b32_e32 v51, v223
	v_mov_b32_e32 v52, v224
	v_mov_b32_e32 v53, v225
	global_load_dwordx4 v[222:225], v[250:251], off offset:192 nt
	v_lshlrev_b32_e32 v91, 16, v50
	v_and_b32_e32 v50, 0xffff0000, v50
	v_lshlrev_b32_e32 v92, 16, v51
	v_and_b32_e32 v51, 0xffff0000, v51
	v_lshlrev_b32_e32 v93, 16, v52
	v_and_b32_e32 v52, 0xffff0000, v52
	v_lshlrev_b32_e32 v94, 16, v53
	v_and_b32_e32 v53, 0xffff0000, v53
	s_waitcnt lgkmcnt(1)
	v_mul_f32_e32 v32, v32, v91
	v_mul_f32_e32 v33, v33, v50
	v_mul_f32_e32 v34, v34, v92
	v_mul_f32_e32 v35, v35, v51
	s_waitcnt lgkmcnt(0)
	v_mul_f32_e32 v36, v36, v93
	v_mul_f32_e32 v37, v37, v52
	v_mul_f32_e32 v38, v38, v94
	v_mul_f32_e32 v39, v39, v53
	v_cvt_pk_bf16_f32 v32, v32, v33
	v_cvt_pk_bf16_f32 v33, v34, v35
	v_cvt_pk_bf16_f32 v34, v36, v37
	v_cvt_pk_bf16_f32 v35, v38, v39
	global_store_dwordx4 v[54:55], v[32:35], off
	s_waitcnt lgkmcnt(0)
	ds_write2_b32 v86, v49, v60 offset1:32
	ds_write2_b32 v86, v61, v62 offset0:64 offset1:96
	ds_write2_b32 v87, v63, v68 offset1:32
	ds_write2_b32 v87, v69, v90 offset0:64 offset1:96
	ds_write2_b32 v88, v40, v41 offset1:32
	ds_write2_b32 v88, v42, v43 offset0:64 offset1:96
	ds_write2_b32 v89, v44, v45 offset1:32
	ds_write2_b32 v89, v46, v47 offset0:64 offset1:96
	s_waitcnt lgkmcnt(0)
	ds_read_b128 v[36:39], v48 offset:16384
	ds_read_b128 v[40:43], v48 offset:16400
	v_lshl_add_u64 v[44:45], v[58:59], 0, s[2:3]
	v_lshl_add_u64 v[46:47], v[56:57], 0, s[2:3]
	s_waitcnt vmcnt(7)
	v_mov_b32_e32 v32, v226
	v_mov_b32_e32 v33, v227
	v_mov_b32_e32 v34, v228
	v_mov_b32_e32 v35, v229
	v_lshlrev_b32_e32 v49, 16, v32
	v_and_b32_e32 v32, 0xffff0000, v32
	v_lshlrev_b32_e32 v50, 16, v33
	v_and_b32_e32 v33, 0xffff0000, v33
	v_lshlrev_b32_e32 v51, 16, v34
	v_and_b32_e32 v34, 0xffff0000, v34
	v_lshlrev_b32_e32 v52, 16, v35
	v_and_b32_e32 v35, 0xffff0000, v35
	s_waitcnt lgkmcnt(1)
	v_mul_f32_e32 v32, v37, v32
	v_mul_f32_e32 v33, v39, v33
	s_waitcnt lgkmcnt(0)
	v_mul_f32_e32 v34, v41, v34
	v_mul_f32_e32 v35, v43, v35
	v_mul_f32_e32 v36, v36, v49
	v_mul_f32_e32 v37, v38, v50
	v_mul_f32_e32 v38, v40, v51
	v_mul_f32_e32 v39, v42, v52
	v_cvt_pk_bf16_f32 v32, v36, v32
	v_cvt_pk_bf16_f32 v33, v37, v33
	v_cvt_pk_bf16_f32 v34, v38, v34
	v_cvt_pk_bf16_f32 v35, v39, v35
	global_store_dwordx4 v[58:59], v[32:35], off offset:64
	v_mul_f32_e32 v40, v16, v72
	v_mul_f32_e32 v41, v17, v73
	v_mul_f32_e32 v42, v18, v74
	v_mul_f32_e32 v43, v19, v75
	v_mul_f32_e32 v46, v20, v76
	v_mul_f32_e32 v47, v21, v77
	v_mul_f32_e32 v49, v22, v78
	v_mul_f32_e32 v50, v23, v79
	ds_read_b128 v[16:19], v48 offset:18432
	ds_read_b128 v[20:23], v48 offset:18448
	v_mov_b64_e32 v[36:37], v[66:67]
	v_mov_b64_e32 v[38:39], v[64:65]
	s_waitcnt vmcnt(7)
	v_mov_b32_e32 v32, v230
	v_mov_b32_e32 v33, v231
	v_mov_b32_e32 v34, v232
	v_mov_b32_e32 v35, v233
	v_lshlrev_b32_e32 v51, 16, v32
	v_and_b32_e32 v32, 0xffff0000, v32
	v_lshlrev_b32_e32 v52, 16, v33
	v_and_b32_e32 v33, 0xffff0000, v33
	v_lshlrev_b32_e32 v53, 16, v34
	v_and_b32_e32 v34, 0xffff0000, v34
	v_lshlrev_b32_e32 v54, 16, v35
	v_and_b32_e32 v35, 0xffff0000, v35
	s_waitcnt lgkmcnt(1)
	v_mul_f32_e32 v16, v16, v51
	v_mul_f32_e32 v17, v17, v32
	v_mul_f32_e32 v18, v18, v52
	v_mul_f32_e32 v19, v19, v33
	s_waitcnt lgkmcnt(0)
	v_mul_f32_e32 v20, v20, v53
	v_mul_f32_e32 v21, v21, v34
	v_mul_f32_e32 v22, v22, v54
	v_mul_f32_e32 v23, v23, v35
	v_cvt_pk_bf16_f32 v16, v16, v17
	v_cvt_pk_bf16_f32 v17, v18, v19
	v_cvt_pk_bf16_f32 v18, v20, v21
	v_cvt_pk_bf16_f32 v19, v22, v23
	global_store_dwordx4 v[44:45], v[16:19], off offset:64
	s_waitcnt lgkmcnt(0)
	ds_write2_b32 v86, v40, v41 offset1:32
	ds_write2_b32 v86, v42, v43 offset0:64 offset1:96
	ds_write2_b32 v87, v46, v47 offset1:32
	ds_write2_b32 v87, v49, v50 offset0:64 offset1:96
	ds_write2_b32 v88, v24, v25 offset1:32
	ds_write2_b32 v88, v26, v27 offset0:64 offset1:96
	ds_write2_b32 v89, v28, v29 offset1:32
	ds_write2_b32 v89, v30, v31 offset0:64 offset1:96
	s_waitcnt lgkmcnt(0)
	ds_read_b128 v[20:23], v48 offset:16384
	ds_read_b128 v[24:27], v48 offset:16400
	v_lshl_add_u64 v[28:29], v[38:39], 0, s[2:3]
	v_lshl_add_u64 v[30:31], v[36:37], 0, s[2:3]
	s_waitcnt vmcnt(7)
	v_mov_b32_e32 v16, v234
	v_mov_b32_e32 v17, v235
	v_mov_b32_e32 v18, v236
	v_mov_b32_e32 v19, v237
	v_lshlrev_b32_e32 v32, 16, v16
	v_and_b32_e32 v16, 0xffff0000, v16
	v_lshlrev_b32_e32 v33, 16, v17
	v_and_b32_e32 v17, 0xffff0000, v17
	v_lshlrev_b32_e32 v34, 16, v18
	v_and_b32_e32 v18, 0xffff0000, v18
	v_lshlrev_b32_e32 v35, 16, v19
	v_and_b32_e32 v19, 0xffff0000, v19
	s_waitcnt lgkmcnt(1)
	v_mul_f32_e32 v16, v21, v16
	v_mul_f32_e32 v17, v23, v17
	s_waitcnt lgkmcnt(0)
; #define LAS __attribute__((address_space(3)))
; __device__ __forceinline__ unsigned cvt_pk_bf16(float lo, float hi) { unsigned r; asm volatile("v_cvt_pk_bf16_f32 %0, %1, %2" : "=v"(r) : "v"(lo), "v"(hi)); return r; }
; __device__ __forceinline__ float bf_lo(unsigned w) { return __uint_as_float(w << 16); }
; __device__ __forceinline__ float bf_hi(unsigned w) { return __uint_as_float(w & 0xffff0000u); }
; __device__ __forceinline__ int crow(int r, int hi) { return (r & 3) + 8 * (r >> 2) + 4 * hi; }
; #define WAITV_BAR(N) asm volatile("s_waitcnt vmcnt(" #N ") lgkmcnt(0)\n\ts_barrier" ::: "memory")
; __device__ __forceinline__ void fox_block(const BlockRef& cur, const BlockRef& nxt, char* lds, Seam& S, const int tid) {
;     ...
;     for (int d0 = 0; d0 < 4; ++d0) {
; #pragma unroll
;         for (int r = 0; r < 16; ++r) stg[crow(r, hi) * 32 + r32] = o[d0][r] * rli[r];
;         asm volatile("s_waitcnt lgkmcnt(0)" ::: "memory");
;         gbf16* op = obase; const gbf16* zp = zbase;
; #pragma unroll
;         for (int i = 0; i < 2; ++i) {
;             asm volatile("" : "+v"(op), "+v"(zp));
;             const f32x4 v0 = *(const LAS f32x4*)(stg + (er + 16 * i) * 32 + 8 * eq), v1 = *(const LAS f32x4*)(stg + (er + 16 * i) * 32 + 8 * eq + 4);
;             const u32x4 z = __builtin_nontemporal_load((const gu32x4*)(zp + d0 * 32));
;             u32x4 w; w.x = cvt_pk_bf16(v0.x * bf_lo(z.x), v0.y * bf_hi(z.x)); w.y = cvt_pk_bf16(v0.z * bf_lo(z.y), v0.w * bf_hi(z.y));
;             w.z = cvt_pk_bf16(v1.x * bf_lo(z.z), v1.y * bf_hi(z.z)); w.w = cvt_pk_bf16(v1.z * bf_lo(z.w), v1.w * bf_hi(z.w));
;             *(gu32x4*)(op + d0 * 32) = w;
;             op += 16 * LD; zp += 16 * LD; }
;         asm volatile("s_waitcnt lgkmcnt(0)" ::: "memory"); }
;     WAITV_BAR(0);
	v_mul_f32_e32 v18, v25, v18
	v_mul_f32_e32 v19, v27, v19
	v_mul_f32_e32 v20, v20, v32
	v_mul_f32_e32 v21, v22, v33
	v_mul_f32_e32 v22, v24, v34
	v_mul_f32_e32 v23, v26, v35
	v_cvt_pk_bf16_f32 v16, v20, v16
	v_cvt_pk_bf16_f32 v17, v21, v17
	v_cvt_pk_bf16_f32 v18, v22, v18
	v_cvt_pk_bf16_f32 v19, v23, v19
	global_store_dwordx4 v[38:39], v[16:19], off offset:128
	v_mul_f32_e32 v20, v0, v72
	v_mul_f32_e32 v21, v1, v73
	v_mul_f32_e32 v22, v2, v74
	v_mul_f32_e32 v23, v3, v75
	v_mul_f32_e32 v24, v4, v76
	v_mul_f32_e32 v25, v5, v77
	v_mul_f32_e32 v26, v6, v78
	v_mul_f32_e32 v27, v7, v79
	ds_read_b128 v[0:3], v48 offset:18432
	ds_read_b128 v[4:7], v48 offset:18448
	s_waitcnt vmcnt(7)
	v_mov_b32_e32 v16, v238
	v_mov_b32_e32 v17, v239
	v_mov_b32_e32 v18, v240
	v_mov_b32_e32 v19, v241
	v_lshlrev_b32_e32 v30, 16, v16
	v_and_b32_e32 v16, 0xffff0000, v16
	v_lshlrev_b32_e32 v31, 16, v17
	v_and_b32_e32 v17, 0xffff0000, v17
	v_lshlrev_b32_e32 v32, 16, v18
	v_and_b32_e32 v18, 0xffff0000, v18
	v_lshlrev_b32_e32 v33, 16, v19
	v_and_b32_e32 v19, 0xffff0000, v19
	s_waitcnt lgkmcnt(1)
	v_mul_f32_e32 v0, v0, v30
	v_mul_f32_e32 v1, v1, v16
	v_mul_f32_e32 v2, v2, v31
	v_mul_f32_e32 v3, v3, v17
	s_waitcnt lgkmcnt(0)
	v_mul_f32_e32 v4, v4, v32
	v_mul_f32_e32 v5, v5, v18
	v_mul_f32_e32 v6, v6, v33
	v_mul_f32_e32 v7, v7, v19
	v_cvt_pk_bf16_f32 v0, v0, v1
	v_cvt_pk_bf16_f32 v1, v2, v3
	v_cvt_pk_bf16_f32 v2, v4, v5
	v_cvt_pk_bf16_f32 v3, v6, v7
	global_store_dwordx4 v[28:29], v[0:3], off offset:128
	s_waitcnt lgkmcnt(0)
	ds_write2_b32 v86, v20, v21 offset1:32
	ds_write2_b32 v86, v22, v23 offset0:64 offset1:96
	ds_write2_b32 v87, v24, v25 offset1:32
	ds_write2_b32 v87, v26, v27 offset0:64 offset1:96
	ds_write2_b32 v88, v8, v9 offset1:32
	ds_write2_b32 v88, v10, v11 offset0:64 offset1:96
	ds_write2_b32 v89, v12, v13 offset1:32
	ds_write2_b32 v89, v14, v15 offset0:64 offset1:96
	s_waitcnt lgkmcnt(0)
	ds_read_b128 v[4:7], v48 offset:16384
	ds_read_b128 v[8:11], v48 offset:16400
	v_lshl_add_u64 v[12:13], v[64:65], 0, s[2:3]
	v_lshl_add_u64 v[14:15], v[66:67], 0, s[2:3]
	v_readfirstlane_b32 s3, v155
	s_ashr_i32 s70, s3, 6
	s_lshl_b32 s5, s70, 7
	s_and_b32 s3, s3, 0x3fffffc0
	v_readlane_b32 s2, v248, 61
	s_lshl_b32 s3, s3, 2
	s_and_b32 s2, s2, 0x700
	s_lshl_b32 s71, s70, 5
	s_add_i32 s3, s3, 0
	s_add_i32 s3, s3, 0x18000
	s_waitcnt vmcnt(7)
	v_mov_b32_e32 v0, v242
	v_mov_b32_e32 v1, v243
	v_mov_b32_e32 v2, v244
	v_mov_b32_e32 v3, v245
	v_lshlrev_b32_e32 v16, 16, v0
	v_and_b32_e32 v0, 0xffff0000, v0
	v_lshlrev_b32_e32 v17, 16, v1
	v_and_b32_e32 v1, 0xffff0000, v1
	v_lshlrev_b32_e32 v18, 16, v2
	v_and_b32_e32 v2, 0xffff0000, v2
	v_lshlrev_b32_e32 v19, 16, v3
	v_and_b32_e32 v3, 0xffff0000, v3
	s_waitcnt lgkmcnt(1)
	v_mul_f32_e32 v0, v5, v0
	v_mul_f32_e32 v1, v7, v1
	s_waitcnt lgkmcnt(0)
	v_mul_f32_e32 v2, v9, v2
	v_mul_f32_e32 v3, v11, v3
	v_mul_f32_e32 v4, v4, v16
	v_mul_f32_e32 v5, v6, v17
	v_mul_f32_e32 v6, v8, v18
	v_mul_f32_e32 v7, v10, v19
	v_cvt_pk_bf16_f32 v0, v4, v0
	v_cvt_pk_bf16_f32 v1, v5, v1
	v_cvt_pk_bf16_f32 v2, v6, v2
	v_cvt_pk_bf16_f32 v3, v7, v3
	global_store_dwordx4 v[64:65], v[0:3], off offset:192
	v_or_b32_e32 v4, s5, v198
	s_ashr_i32 s5, s5, 4
	v_bitop3_b32 v36, s5, -13, v191 bitop3:0xc8
	s_lshr_b32 s5, s5, 1
	v_ashrrev_i32_e32 v5, 4, v4
	s_and_b32 s5, s5, 4
	v_or_b32_e32 v14, 64, v4
	v_bitop3_b32 v4, v5, v203, 15 bitop3:0x6c
	v_lshlrev_b32_e32 v5, 8, v5
	v_or3_b32 v6, v36, s5, v200
	v_lshl_or_b32 v128, v4, 4, v5
	v_lshlrev_b32_e32 v17, 8, v6
	ds_read_b128 v[4:7], v48 offset:18432
	ds_read_b128 v[8:11], v48 offset:18448
	v_ashrrev_i32_e32 v15, 4, v14
	v_bitop3_b32 v16, v15, v203, 15 bitop3:0x6c
	v_or_b32_e32 v134, v17, v204
	s_waitcnt vmcnt(6)
	v_mov_b32_e32 v0, v222
	v_mov_b32_e32 v1, v223
	v_mov_b32_e32 v2, v224
	v_mov_b32_e32 v3, v225
	v_lshlrev_b32_e32 v18, 16, v0
	v_and_b32_e32 v0, 0xffff0000, v0
	v_lshlrev_b32_e32 v19, 16, v1
	v_and_b32_e32 v1, 0xffff0000, v1
	v_lshlrev_b32_e32 v20, 16, v2
	v_and_b32_e32 v2, 0xffff0000, v2
	v_lshlrev_b32_e32 v21, 16, v3
	v_and_b32_e32 v3, 0xffff0000, v3
	s_waitcnt lgkmcnt(1)
	v_mul_f32_e32 v0, v5, v0
	v_mul_f32_e32 v1, v7, v1
	s_waitcnt lgkmcnt(0)
	v_mul_f32_e32 v2, v9, v2
	v_mul_f32_e32 v3, v11, v3
	v_mul_f32_e32 v4, v4, v18
	v_mul_f32_e32 v5, v6, v19
	v_mul_f32_e32 v6, v8, v20
	v_mul_f32_e32 v7, v10, v21
	v_cvt_pk_bf16_f32 v0, v4, v0
	v_cvt_pk_bf16_f32 v1, v5, v1
	v_cvt_pk_bf16_f32 v2, v6, v2
	v_cvt_pk_bf16_f32 v3, v7, v3
	global_store_dwordx4 v[12:13], v[0:3], off offset:192
	s_waitcnt lgkmcnt(0)
	s_waitcnt vmcnt(8) lgkmcnt(0)
	s_barrier
; #define LAS __attribute__((address_space(3)))
; __device__ __forceinline__ void partialSM(f32x16& p0, f32x16& p1, float& m_reg, float& mn, float& alpha) {
;     float pmax = p0[0];
; #pragma unroll
;     for (int r = 1; r < 16; ++r) pmax = fmaxf(pmax, p0[r]);
; #pragma unroll
;     for (int r = 0; r < 16; ++r) pmax = fmaxf(pmax, p1[r]);
;     { auto rr = __builtin_amdgcn_permlane32_swap(__float_as_uint(pmax), __float_as_uint(pmax), false, false);
;       pmax = fmaxf(__uint_as_float(rr[0]), __uint_as_float(rr[1])); }
;     if (__builtin_expect(__all((pmax - m_reg) <= THR2), 1)) { mn = m_reg; alpha = 1.f; }
;     else { mn = fmaxf(m_reg, pmax); alpha = __builtin_amdgcn_exp2f(m_reg - mn); m_reg = mn; }
; #pragma unroll
;     for (int r = 0; r < 16; ++r) p0[r] = p0[r] - mn;
; #pragma unroll
;     for (int r = 0; r < 16; ++r) p1[r] = p1[r] - mn;
; #pragma unroll
;     for (int r = 0; r < 16; ++r) p0[r] = __builtin_amdgcn_exp2f(p0[r]);
; }
; __device__ __forceinline__ void qkt(f32x16& p0, f32x16& p1, const char* Kslot, int r32, int hi, const bf16x8* qr, const LAS f32x4* cp) {
; #pragma unroll
;     for (int g = 0; g < 4; ++g) { const f32x4 c0 = cp[2 * g], c1 = cp[8 + 2 * g];
; #pragma unroll
;         for (int j = 0; j < 4; ++j) { p0[4 * g + j] = c0[j]; p1[4 * g + j] = c1[j]; } }
;     const char* kb[4];
; #pragma unroll
;     for (int dd = 0; dd < 4; ++dd) kb[dd] = Kslot + KSWZ(r32, (dd * 16 + hi * 8) * 2);
; #pragma unroll
;     for (int d0 = 0; d0 < 8; ++d0) { const char* a = kb[d0 & 3] + (d0 >> 2) * 128;
;         bf16x8 b0 = *reinterpret_cast<const bf16x8*>(a);
;         bf16x8 b1 = *reinterpret_cast<const bf16x8*>(a + 32 * 256);
;         p0 = __builtin_amdgcn_mfma_f32_32x32x16_bf16(b0, qr[d0], p0, 0, 0, 0);
;         p1 = __builtin_amdgcn_mfma_f32_32x32x16_bf16(b1, qr[d0], p1, 0, 0, 0); }
; }
	s_nop 1
	v_lshlrev_b32_e32 v0, 8, v15
	v_lshl_or_b32 v138, v16, 4, v0
	v_and_or_b32 v0, v14, s6, v202
	v_lshl_or_b32 v136, v0, 1, v17
	s_lshl_b32 s6, s70, 11
	s_add_i32 s86, s6, 0
	s_add_i32 m0, s86, 0x14000
	v_readlane_b32 s6, v247, 24
	global_load_lds_dwordx4 v128, s[66:67]
	s_add_i32 m0, s86, 0x14400
	v_readlane_b32 s7, v247, 25
	global_load_lds_dwordx4 v138, s[66:67]
	s_add_i32 m0, s86, 0x4000
	v_mov_b32_e32 v139, v129
	s_add_i32 s88, s71, s4
	s_nop 0
	global_load_lds_dwordx4 v134, s[6:7]
	s_add_i32 m0, s86, 0x4400
	s_movk_i32 s73, 0x4000
	global_load_lds_dwordx4 v136, s[6:7]
	v_mov_b32_e32 v135, v129
	v_mov_b32_e32 v137, v129
	s_add_i32 s89, s89, 4
	ds_read_b128 v[16:19], v209 offset:57344
	ds_read_b128 v[0:3], v205 offset:128
	ds_read_b128 v[4:7], v205 offset:160
	ds_read_b128 v[8:11], v205 offset:192
	ds_read_b128 v[12:15], v205 offset:224
	v_xor_b32_e32 v249, 0x80, v209
	v_xor_b32_e32 v250, 0x80, v208
	v_xor_b32_e32 v251, 0x80, v207
	v_xor_b32_e32 v252, 0x80, v206
	ds_read_b128 v[20:23], v249 offset:57344
	s_mov_b32 s4, 0xff800000
	s_waitcnt lgkmcnt(0)
	v_mfma_f32_32x32x16_bf16 v[0:15], v[16:19], v[96:99], v[0:15]
	ds_read_b128 v[16:19], v208 offset:57344
	ds_read_b128 v[24:27], v250 offset:57344
	s_waitcnt lgkmcnt(0)
	v_mfma_f32_32x32x16_bf16 v[0:15], v[16:19], v[100:103], v[0:15]
	ds_read_b128 v[16:19], v207 offset:57344
	ds_read_b128 v[28:31], v251 offset:57344
	s_waitcnt lgkmcnt(0)
	v_mfma_f32_32x32x16_bf16 v[0:15], v[16:19], v[104:107], v[0:15]
	ds_read_b128 v[16:19], v206 offset:57344
	ds_read_b128 v[32:35], v252 offset:57344
	s_waitcnt lgkmcnt(0)
	v_mfma_f32_32x32x16_bf16 v[0:15], v[16:19], v[108:111], v[0:15]
	v_mfma_f32_32x32x16_bf16 v[0:15], v[20:23], v[112:115], v[0:15]
	v_mfma_f32_32x32x16_bf16 v[0:15], v[24:27], v[116:119], v[0:15]
	v_mfma_f32_32x32x16_bf16 v[0:15], v[28:31], v[120:123], v[0:15]
	v_mfma_f32_32x32x16_bf16 v[0:15], v[32:35], v[124:127], v[0:15]
	s_nop 11
	v_max3_f32 v0, v8, s4, v9
	v_max3_f32 v0, v0, v10, v11
	v_max3_f32 v0, v0, v12, v13
	v_max3_f32 v0, v0, v14, v15
	v_mov_b32_e32 v1, v0
	s_nop 1
	v_permlane32_swap_b32_e32 v0, v1
	v_max_f32_e32 v1, v1, v1
	v_max_f32_e32 v0, v0, v0
	v_max_f32_e32 v0, v0, v1
	v_add_f32_e32 v1, 0x7149f2ca, v0
	v_cmp_ge_f32_e32 vcc, s33, v1
	s_cmp_eq_u64 vcc, exec
	v_max_f32_e32 v2, 0xf149f2ca, v0
	s_cselect_b64 vcc, -1, 0
	v_cndmask_b32_e32 v144, v2, v189, vcc
	v_mov_b32_e32 v0, v9
	v_mov_b32_e32 v1, v10
	v_pk_add_f32 v[66:67], v[0:1], v[144:145] op_sel_hi:[1,0] neg_lo:[0,1] neg_hi:[0,1]
	v_mov_b32_e32 v0, v11
	v_mov_b32_e32 v1, v12
	v_pk_add_f32 v[68:69], v[0:1], v[144:145] op_sel_hi:[1,0] neg_lo:[0,1] neg_hi:[0,1]
	v_sub_f32_e32 v1, 0xf149f2ca, v2
	v_mov_b32_e32 v131, v8
	v_mov_b32_e32 v0, v13
	v_exp_f32_e32 v2, v1
	v_mov_b32_e32 v1, v14
	s_add_i32 s2, s2, s71
	v_pk_add_f32 v[64:65], v[130:131], v[144:145] op_sel_hi:[1,0] neg_lo:[0,1] neg_hi:[0,1]
	v_pk_add_f32 v[70:71], v[0:1], v[144:145] op_sel_hi:[1,0] neg_lo:[0,1] neg_hi:[0,1]
	v_or_b32_e32 v0, s2, v199
	v_exp_f32_e32 v178, v64
	v_sub_u32_e32 v173, v0, v201
	v_add_u32_e32 v0, v36, v200
	v_add_lshl_u32 v0, v0, s5, 8
	s_waitcnt vmcnt(4) lgkmcnt(0)
	s_barrier
	v_or_b32_e32 v1, v0, v211
	v_mov_b32_e32 v48, v129
	v_mov_b32_e32 v49, v129
	v_sub_f32_e32 v155, v15, v144
	v_cndmask_b32_e64 v174, v2, 1.0, vcc
	v_add_u32_e32 v140, v1, v210
	v_or3_b32 v142, v0, v212, v210
	v_mov_b32_e32 v50, v129
	v_mov_b32_e32 v51, v129
	v_mov_b32_e32 v52, v129
	v_mov_b32_e32 v53, v129
	v_mov_b32_e32 v54, v129
	v_mov_b32_e32 v55, v129
	v_mov_b32_e32 v56, v129
	v_mov_b32_e32 v57, v129
	v_mov_b32_e32 v58, v129
	v_mov_b32_e32 v59, v129
	v_mov_b32_e32 v60, v129
	v_mov_b32_e32 v61, v129
	v_mov_b32_e32 v62, v129
	v_mov_b32_e32 v63, v129
	v_mov_b64_e32 v[32:33], v[48:49]
	v_mov_b64_e32 v[16:17], v[48:49]
	v_mov_b64_e32 v[0:1], v[48:49]
	v_add_u32_e32 v171, s3, v133
	v_lshl_add_u32 v131, v201, 2, s3
	v_mov_b32_e32 v141, v129
	v_mov_b32_e32 v143, v129
	s_mov_b32 s2, 0
	v_mov_b32_e32 v172, 0
	s_mov_b32 s90, 0x8000
	s_movk_i32 s91, 0xbf
	v_mov_b64_e32 v[34:35], v[50:51]
	v_mov_b64_e32 v[36:37], v[52:53]
	v_mov_b64_e32 v[38:39], v[54:55]
	v_mov_b64_e32 v[40:41], v[56:57]
	v_mov_b64_e32 v[42:43], v[58:59]
	v_mov_b64_e32 v[44:45], v[60:61]
	v_mov_b64_e32 v[46:47], v[62:63]
	v_mov_b64_e32 v[18:19], v[50:51]
	v_mov_b64_e32 v[20:21], v[52:53]
	v_mov_b64_e32 v[22:23], v[54:55]
	v_mov_b64_e32 v[24:25], v[56:57]
	v_mov_b64_e32 v[26:27], v[58:59]
	v_mov_b64_e32 v[28:29], v[60:61]
	v_mov_b64_e32 v[30:31], v[62:63]
	v_mov_b64_e32 v[2:3], v[50:51]
	v_mov_b64_e32 v[4:5], v[52:53]
	v_mov_b64_e32 v[6:7], v[54:55]
	v_mov_b64_e32 v[8:9], v[56:57]
	v_mov_b64_e32 v[10:11], v[58:59]
	v_mov_b64_e32 v[12:13], v[60:61]
	v_mov_b64_e32 v[14:15], v[62:63]
	s_mov_b32 s72, 0
	v_mov_b32_e32 v211, v178
	v_mov_b32_e32 v208, v178
	v_mov_b32_e32 v210, v178
	v_mov_b32_e32 v206, v178
	v_mov_b32_e32 v209, v178
	v_mov_b32_e32 v205, v178
	v_mov_b32_e32 v207, v178
	v_mov_b32_e32 v202, v178
	v_mov_b32_e32 v204, v178
	v_mov_b32_e32 v200, v178
	v_mov_b32_e32 v203, v178
	v_mov_b32_e32 v198, v178
	v_mov_b32_e32 v201, v178
	v_mov_b32_e32 v179, v178
	v_mov_b32_e32 v199, v178
	v_mov_b32_e32 v158, v64
	v_mov_b32_e32 v159, v64
	v_mov_b32_e32 v162, v64
	v_mov_b32_e32 v163, v64
	v_mov_b32_e32 v166, v64
	v_mov_b32_e32 v167, v64
	v_mov_b32_e32 v156, v64
	v_mov_b32_e32 v157, v64
	v_mov_b32_e32 v160, v65
	v_mov_b32_e32 v161, v66
	v_mov_b32_e32 v164, v67
	v_mov_b32_e32 v165, v68
	v_mov_b32_e32 v168, v69
	v_mov_b32_e32 v169, v70
	v_mov_b32_e32 v154, v71
	v_readlane_b32 s96, v247, 9
	v_readlane_b32 s97, v247, 8
